# weight-tile warm-up: waves 1..7 touch the first four K-tiles of the next GEMM phase's first B tile (LDS-DMA into idle stage area) while the workgroup sits in the sibling barrier
# baseline (speedup 1.0000x reference)
.LBB0_78:
	s_or_b64 exec, exec, s[4:5]
	s_getreg_b32 s8, hwreg(HW_REG_XCC_ID, 0, 4)
	s_waitcnt vmcnt(0)
	v_readfirstlane_b32 s10, v154
	s_lshr_b32 s10, s10, 6
	s_cmp_eq_u32 s10, 0
	s_cbranch_scc1 .Ltw_skip_b1
	v_readlane_b32 s11, v253, 0
	s_lshr_b32 s11, s11, 6
	s_mul_i32 s11, s11, 0x80000
	v_readlane_b32 s12, v254, 57
	s_bitcmp1_b32 s12, 0
	s_cselect_b32 s12, 0x3680000, 0
	s_add_u32 s11, s11, s12
	s_add_u32 s12, s72, 0x0
	s_addc_u32 s13, s73, 0
	s_add_u32 s12, s12, s11
	s_addc_u32 s13, s13, 0
	v_subrev_u32_e32 v172, 64, v154
	v_lshrrev_b32_e32 v174, 1, v172
	v_and_b32_e32 v172, 1, v172
	v_mul_u32_u24_e32 v174, 0x800, v174
	v_lshl_add_u32 v172, v172, 7, v174
	v_add_u32_e32 v174, 0x100, v172
	s_lshl_b32 s10, s10, 10
	s_mov_b32 m0, s10
	s_nop 0
	global_load_lds_dwordx4 v172, s[12:13]
	global_load_lds_dwordx4 v174, s[12:13]
.Ltw_skip_b1:
	s_barrier
	s_mov_b64 s[4:5], exec
	v_readlane_b32 s6, v253, 9
	v_readlane_b32 s7, v253, 10
	s_and_b64 s[6:7], s[4:5], s[6:7]
	s_mov_b64 exec, s[6:7]
	s_cbranch_execz .LBB0_108
	v_readlane_b32 s9, v254, 57
	s_cmp_eq_u32 s9, 0
	s_cbranch_scc1 .Llb_grid_b1
	v_readlane_b32 s8, v253, 43
	v_readlane_b32 s9, v253, 44
	v_readlane_b32 s10, v253, 0
	ds_read_b32 v5, v156 offset:8
	s_and_b32 s10, s10, 63
	s_lshl_b32 s10, s10, 2
	v_mov_b32_e32 v0, s10
	v_mov_b32_e32 v1, 1
	s_waitcnt vmcnt(0) lgkmcnt(0)
	v_readfirstlane_b32 s11, v5
	s_cmp_eq_u32 s11, 0
	s_cbranch_scc1 .Llb_rel_b1
	buffer_wbl2 sc1
	s_waitcnt vmcnt(0)

.Lconv_ret1:
	s_getreg_b32 s8, hwreg(HW_REG_XCC_ID, 0, 4)
	s_waitcnt vmcnt(0)
	s_waitcnt vmcnt(0)
	v_readfirstlane_b32 s10, v154
	s_lshr_b32 s10, s10, 6
	s_cmp_eq_u32 s10, 0
	s_cbranch_scc1 .Ltw_skip_b2
	v_readlane_b32 s11, v253, 0
	s_lshr_b32 s11, s11, 6
	s_mul_i32 s11, s11, 0x160000
	v_readlane_b32 s12, v254, 57
	s_bitcmp1_b32 s12, 0
	s_cselect_b32 s12, 0x3680000, 0
	s_add_u32 s11, s11, s12
	s_add_u32 s12, s72, 0xb00000
	s_addc_u32 s13, s73, 0
	s_add_u32 s12, s12, s11
	s_addc_u32 s13, s13, 0
	v_subrev_u32_e32 v172, 64, v154
	v_lshrrev_b32_e32 v174, 1, v172
	v_and_b32_e32 v172, 1, v172
	v_mul_u32_u24_e32 v174, 0x1600, v174
	v_lshl_add_u32 v172, v172, 7, v174
	v_add_u32_e32 v174, 0x100, v172
	s_lshl_b32 s10, s10, 10
	s_mov_b32 m0, s10
	s_nop 0
	global_load_lds_dwordx4 v172, s[12:13]
	global_load_lds_dwordx4 v174, s[12:13]
.Ltw_skip_b2:
	s_barrier
	s_mov_b64 s[4:5], exec
	v_readlane_b32 s6, v253, 9
	v_readlane_b32 s7, v253, 10
	s_and_b64 s[6:7], s[4:5], s[6:7]
	s_mov_b64 exec, s[6:7]
	s_cbranch_execz .LBB0_147
	v_readlane_b32 s8, v253, 43
	v_readlane_b32 s9, v253, 44
	v_readlane_b32 s10, v253, 0
	ds_read_b32 v5, v156 offset:8
	s_and_b32 s10, s10, 63
	s_lshl_b32 s10, s10, 2
	v_mov_b32_e32 v0, s10
	v_mov_b32_e32 v1, 1
	s_waitcnt vmcnt(0) lgkmcnt(0)
	v_readfirstlane_b32 s11, v5
	s_cmp_eq_u32 s11, 0
	s_cbranch_scc1 .Llb_rel_b2
	buffer_wbl2 sc1
	s_waitcnt vmcnt(0)

.LBB0_189:
	s_or_b64 exec, exec, s[0:1]
	s_getreg_b32 s6, hwreg(HW_REG_XCC_ID, 0, 4)
	s_waitcnt vmcnt(0)
	v_readfirstlane_b32 s10, v154
	s_lshr_b32 s10, s10, 6
	s_cmp_eq_u32 s10, 0
	s_cbranch_scc1 .Ltw_skip_b4
	v_readlane_b32 s11, v253, 0
	s_lshr_b32 s11, s11, 6
	s_mul_i32 s11, s11, 0x80000
	v_readlane_b32 s12, v254, 57
	s_bitcmp1_b32 s12, 0
	s_cselect_b32 s12, 0x3680000, 0
	s_add_u32 s11, s11, s12
	s_add_u32 s12, s72, 0x1080000
	s_addc_u32 s13, s73, 0
	s_add_u32 s12, s12, s11
	s_addc_u32 s13, s13, 0
	v_subrev_u32_e32 v172, 64, v154
	v_lshrrev_b32_e32 v174, 1, v172
	v_and_b32_e32 v172, 1, v172
	v_mul_u32_u24_e32 v174, 0x800, v174
	v_lshl_add_u32 v172, v172, 7, v174
	v_add_u32_e32 v174, 0x100, v172
	s_lshl_b32 s10, s10, 10
	s_mov_b32 m0, s10
	s_nop 0
	global_load_lds_dwordx4 v172, s[12:13]
	global_load_lds_dwordx4 v174, s[12:13]
.Ltw_skip_b4:
	s_barrier
	s_mov_b64 s[0:1], exec
	v_readlane_b32 s4, v253, 9
	v_readlane_b32 s5, v253, 10
	s_and_b64 s[4:5], s[0:1], s[4:5]
	s_mov_b64 exec, s[4:5]
	s_cbranch_execz .LBB0_219
	v_readlane_b32 s8, v253, 43
	v_readlane_b32 s9, v253, 44
	v_readlane_b32 s10, v253, 0
	ds_read_b32 v5, v156 offset:8
	s_and_b32 s10, s10, 63
	s_lshl_b32 s10, s10, 2
	v_mov_b32_e32 v0, s10
	v_mov_b32_e32 v1, 1
	s_waitcnt vmcnt(0) lgkmcnt(0)
	v_readfirstlane_b32 s11, v5
	s_cmp_eq_u32 s11, 0
	s_cbranch_scc1 .Llb_rel_b4
	buffer_wbl2 sc1
	s_waitcnt vmcnt(0)

.LBB0_555:
	s_getreg_b32 s6, hwreg(HW_REG_XCC_ID, 0, 4)
	s_waitcnt vmcnt(0)
	v_readfirstlane_b32 s10, v154
	s_lshr_b32 s10, s10, 6
	s_cmp_eq_u32 s10, 0
	s_cbranch_scc1 .Ltw_skip_b9
	v_readlane_b32 s11, v253, 0
	s_lshr_b32 s11, s11, 6
	s_mul_i32 s11, s11, 0x80000
	v_readlane_b32 s12, v254, 57
	s_bitcmp1_b32 s12, 0
	s_cselect_b32 s12, 0x3680000, 0
	s_add_u32 s11, s11, s12
	s_add_u32 s12, s72, 0x2400000
	s_addc_u32 s13, s73, 0
	s_add_u32 s12, s12, s11
	s_addc_u32 s13, s13, 0
	v_subrev_u32_e32 v172, 64, v154
	v_lshrrev_b32_e32 v174, 1, v172
	v_and_b32_e32 v172, 1, v172
	v_mul_u32_u24_e32 v174, 0x800, v174
	v_lshl_add_u32 v172, v172, 7, v174
	v_add_u32_e32 v174, 0x100, v172
	s_lshl_b32 s10, s10, 10
	s_mov_b32 m0, s10
	s_nop 0
	global_load_lds_dwordx4 v172, s[12:13]
	global_load_lds_dwordx4 v174, s[12:13]

.LBB0_627:
	s_or_b64 exec, exec, s[0:1]
	s_getreg_b32 s6, hwreg(HW_REG_XCC_ID, 0, 4)
	s_waitcnt vmcnt(0)
	v_readfirstlane_b32 s10, v154
	s_lshr_b32 s10, s10, 6
	s_cmp_eq_u32 s10, 0
	s_cbranch_scc1 .Ltw_skip_b11
	v_readlane_b32 s11, v253, 0
	s_lshr_b32 s11, s11, 6
	s_mul_i32 s11, s11, 0x80000
	v_readlane_b32 s12, v254, 57
	s_bitcmp1_b32 s12, 0
	s_cselect_b32 s12, 0x3680000, 0
	s_add_u32 s11, s11, s12
	s_add_u32 s12, s72, 0x2600000
	s_addc_u32 s13, s73, 0
	s_add_u32 s12, s12, s11
	s_addc_u32 s13, s13, 0
	v_subrev_u32_e32 v172, 64, v154
	v_lshrrev_b32_e32 v174, 1, v172
	v_and_b32_e32 v172, 1, v172
	v_mul_u32_u24_e32 v174, 0x800, v174
	v_lshl_add_u32 v172, v172, 7, v174
	v_add_u32_e32 v174, 0x100, v172
	s_lshl_b32 s10, s10, 10
	s_mov_b32 m0, s10
	s_nop 0
	global_load_lds_dwordx4 v172, s[12:13]
	global_load_lds_dwordx4 v174, s[12:13]

.Lconv_ret3:
	s_getreg_b32 s6, hwreg(HW_REG_XCC_ID, 0, 4)
	s_waitcnt vmcnt(0)
	s_waitcnt vmcnt(0)
	v_readfirstlane_b32 s10, v154
	s_lshr_b32 s10, s10, 6
	s_cmp_eq_u32 s10, 0
	s_cbranch_scc1 .Ltw_skip_b12
	v_readlane_b32 s11, v253, 0
	s_lshr_b32 s11, s11, 6
	s_mul_i32 s11, s11, 0x160000
	v_readlane_b32 s12, v254, 57
	s_bitcmp1_b32 s12, 0
	s_cselect_b32 s12, 0x3680000, 0
	s_add_u32 s11, s11, s12
	s_add_u32 s12, s72, 0x3100000
	s_addc_u32 s13, s73, 0
	s_add_u32 s12, s12, s11
	s_addc_u32 s13, s13, 0
	v_subrev_u32_e32 v172, 64, v154
	v_lshrrev_b32_e32 v174, 1, v172
	v_and_b32_e32 v172, 1, v172
	v_mul_u32_u24_e32 v174, 0x1600, v174
	v_lshl_add_u32 v172, v172, 7, v174
	v_add_u32_e32 v174, 0x100, v172
	s_lshl_b32 s10, s10, 10
	s_mov_b32 m0, s10
	s_nop 0
	global_load_lds_dwordx4 v172, s[12:13]
	global_load_lds_dwordx4 v174, s[12:13]
